# Resid GEMM (DOWN/OUTA/OUTB) visits its pm-tile groups in reverse order so ACT written last by UP is read first (MALL hits)
# speedup vs baseline: 1.0044x; 1.0044x over previous
.LBB0_273:
	s_max_i32 s68, s72, 1
	s_cmp_ge_i32 s68, s73
	s_cbranch_scc1 .LBB0_672
	s_load_dwordx2 s[80:81], s[0:1], 0xf0
	s_load_dwordx2 s[6:7], s[0:1], 0x100
	s_load_dwordx4 s[8:11], s[0:1], 0xe0
	v_mbcnt_lo_u32_b32 v0, -1, 0
	v_mbcnt_hi_u32_b32 v0, -1, v0
	s_waitcnt lgkmcnt(0)
	s_add_u32 s82, s80, 0xa800000
	s_addc_u32 s83, s81, 0
	v_writelane_b32 v253, s8, 3
	s_add_u32 s84, s80, 0x500000
	s_addc_u32 s85, s81, 0
	v_writelane_b32 v253, s9, 4
	v_writelane_b32 v253, s10, 5
	v_writelane_b32 v253, s11, 6
	s_add_u32 s86, s80, 0x100000
	v_readlane_b32 s3, v253, 2
	s_addc_u32 s87, s81, 0
	s_lshl_b32 s2, s3, 3
	s_andn2_b32 s33, s33, 63
	s_add_i32 s2, s46, s2
	s_cmpk_lt_i32 s70, 0x400
	s_cselect_b64 s[88:89], -1, 0
	s_add_u32 s8, s80, 0x1c800000
	s_addc_u32 s9, s81, 0
	v_writelane_b32 v253, s8, 7
	s_mul_i32 s4, s7, s6
	v_add_u32_e32 v238, s33, v0
	v_writelane_b32 v253, s9, 8
	s_add_u32 s8, s80, 0x12800000
	s_addc_u32 s9, s81, 0
	v_writelane_b32 v253, s8, 9
	v_mov_b32_e32 v1, 0
	v_mov_b32_e32 v239, 0x3727c5ac
	v_writelane_b32 v253, s9, 10
	s_add_u32 s8, s80, 0x14800000
	s_addc_u32 s9, s81, 0
	v_writelane_b32 v253, s8, 11
	s_movk_i32 s95, 0x90
	v_mov_b32_e32 v243, 0xff800000
	v_writelane_b32 v253, s9, 12
	s_add_u32 s8, s80, 0x2c800000
	s_addc_u32 s9, s81, 0
	v_writelane_b32 v253, s8, 13
	s_cmp_lt_i32 s2, 0x10000
	v_mov_b32_e32 v245, 0x3e38aa3b
	v_writelane_b32 v253, s9, 14
	v_writelane_b32 v253, s2, 15
	s_cselect_b64 s[8:9], -1, 0
	v_writelane_b32 v253, s8, 16
	s_add_u32 s2, s80, 0x24800000
	s_mov_b32 s67, 0x41000000
	v_writelane_b32 v253, s9, 17
	v_writelane_b32 v253, s2, 18
	s_addc_u32 s2, s81, 0
	s_cmpk_lt_i32 s3, 0x400
	v_writelane_b32 v253, s2, 19
	s_cselect_b64 s[2:3], -1, 0
	v_writelane_b32 v253, s2, 20
	s_mov_b32 s79, 0
	s_mov_b64 s[90:91], 0x40000
	v_writelane_b32 v253, s3, 21
	s_add_u32 s2, s80, 0xa200000
	v_writelane_b32 v253, s2, 22
	s_addc_u32 s2, s81, 0
	v_writelane_b32 v253, s2, 23
	s_add_u32 s2, s80, 0x900400
	v_writelane_b32 v253, s2, 24
	s_addc_u32 s2, s81, 0
	v_writelane_b32 v253, s2, 25
	s_add_u32 s2, s80, 0x8e00000
	v_writelane_b32 v253, s2, 26
	s_addc_u32 s2, s81, 0
	v_writelane_b32 v253, s2, 27
	s_add_u32 s2, s80, 0xa600000
	s_addc_u32 s3, s81, 0
	v_writelane_b32 v253, s2, 28
	s_mov_b64 s[74:75], 0x80
	s_mov_b64 s[96:97], 0x20000
	v_writelane_b32 v253, s3, 29
	s_add_u32 s2, s80, 0x900000
	s_addc_u32 s3, s81, 0
	v_writelane_b32 v253, s2, 30
	s_ashr_i32 s72, s70, 3
	s_and_b32 s69, s70, 7
	v_writelane_b32 v253, s3, 31
	s_ashr_i32 s2, s6, 31
	s_and_b32 s7, s72, 7
	v_writelane_b32 v253, s2, 32
	s_ashr_i32 s2, s70, 31
	v_writelane_b32 v253, s2, 33
	s_add_u32 s2, s80, 0x9a00000
	v_writelane_b32 v253, s2, 34
	s_addc_u32 s2, s81, 0
	v_writelane_b32 v253, s2, 35
	s_add_u32 s2, s80, 0x6200000
	v_writelane_b32 v253, s2, 36
	s_addc_u32 s2, s81, 0
	v_writelane_b32 v253, s2, 37
	s_lshl_b32 s2, s70, 7
	s_and_b32 s2, s2, 0x380
	s_add_i32 s2, s2, s72
	s_ashr_i32 s3, s2, 31
	s_lshr_b32 s3, s3, 27
	s_add_i32 s3, s2, s3
	s_ashr_i32 s5, s3, 5
	s_xor_b32 s5, s5, 3
	s_andn2_b32 s3, s3, 31
	s_sub_i32 s2, s2, s3
	s_lshl_b32 s3, s5, 3
	s_or_b32 s3, s3, s7
	v_writelane_b32 v253, s3, 38
	s_ashr_i32 s2, s2, 3
	v_writelane_b32 v253, s2, 39
	s_add_u32 s2, s80, 0xa00000
	v_writelane_b32 v253, s2, 40
	s_addc_u32 s2, s81, 0
	s_cmpk_lt_i32 s70, 0x1600
	v_writelane_b32 v253, s2, 41
	s_cselect_b64 s[2:3], -1, 0
	v_writelane_b32 v253, s2, 42
	s_mov_b64 s[76:77], 0x80000
	s_mov_b64 s[98:99], 0x24840000
	v_writelane_b32 v253, s3, 43
	s_mul_i32 s2, s69, 0x2c0
	s_add_i32 s2, s2, s72
	s_mul_hi_i32 s3, s2, 0x2e8ba2e9
	s_lshr_b32 s5, s3, 31
	s_ashr_i32 s3, s3, 5
	s_add_i32 s3, s3, s5
	s_mul_i32 s5, s3, 0xffffff50
	s_add_i32 s5, s5, s2
	s_lshl_b32 s2, s3, 3
	s_or_b32 s8, s2, s7
	v_writelane_b32 v253, s7, 44
	s_mov_b32 s2, s8
	s_ashr_i32 s10, s5, 3
	s_ashr_i32 s9, s8, 31
	v_writelane_b32 v253, s2, 45
	s_ashr_i32 s11, s10, 31
	s_mov_b64 s[92:93], 0x24840080
	v_writelane_b32 v253, s3, 46
	s_lshl_b64 s[2:3], s[8:9], 19
	s_mov_b32 s8, s10
	v_writelane_b32 v253, s8, 47
	s_nop 1
	v_writelane_b32 v253, s9, 48
	s_lshl_b64 s[8:9], s[10:11], 19
	v_writelane_b32 v253, s8, 49
	s_add_u32 s2, s82, s2
	s_addc_u32 s3, s83, s3
	v_writelane_b32 v253, s9, 50
	s_add_u32 s8, s2, 0x40000
	v_writelane_b32 v253, s2, 51
	s_addc_u32 s9, s3, 0
	s_nop 0
	v_writelane_b32 v253, s3, 52
	s_load_dword s2, s[0:1], 0x108
	v_writelane_b32 v253, s8, 53
	s_waitcnt lgkmcnt(0)
	s_mul_i32 s21, s4, s2
	s_add_u32 s2, s80, 0x200
	s_addc_u32 s3, s81, 0
	v_writelane_b32 v253, s9, 54
	s_add_u32 s22, s80, 0x1000
	v_writelane_b32 v253, s2, 55
	s_addc_u32 s23, s81, 0
	s_mul_i32 s4, s6, 24
	v_writelane_b32 v253, s3, 56
	s_add_u32 s2, s80, 0x1100
	s_addc_u32 s3, s81, 0
	v_writelane_b32 v253, s2, 57
	s_load_dwordx8 s[8:15], s[0:1], 0x68
	s_nop 0
	v_writelane_b32 v253, s3, 58
	s_add_u32 s2, s80, 0x1200
	s_addc_u32 s3, s81, 0
	v_writelane_b32 v253, s2, 59
	s_nop 1
	v_writelane_b32 v253, s3, 60
	s_add_u32 s2, s80, 0x1300
	s_addc_u32 s3, s81, 0
	v_writelane_b32 v253, s2, 61
	s_nop 1
	v_writelane_b32 v253, s3, 62
	s_add_u32 s2, s80, 0x3400
	s_addc_u32 s3, s81, 0
	v_writelane_b32 v253, s2, 63
	s_nop 1
	v_writelane_b32 v254, s3, 0
	s_add_u32 s2, s80, 0x3500
	s_addc_u32 s3, s81, 0
	v_writelane_b32 v254, s2, 1
	s_nop 1
	v_writelane_b32 v254, s3, 2
	s_lshl_b32 s3, s6, 4
	s_load_dwordx2 s[6:7], s[0:1], 0x88
	s_add_i32 s2, 0, 0x20000
	v_writelane_b32 v254, s2, 3
	s_add_i32 s2, 0, 0x20004
	v_writelane_b32 v254, s2, 4
	s_waitcnt lgkmcnt(0)
	v_writelane_b32 v254, s6, 5
	s_nop 1
	v_writelane_b32 v254, s7, 6
	s_load_dwordx2 s[6:7], s[0:1], 0xa0
	s_waitcnt lgkmcnt(0)
	v_writelane_b32 v254, s6, 7
	s_nop 1
	v_writelane_b32 v254, s7, 8
	s_load_dwordx2 s[6:7], s[0:1], 0xb0
	s_waitcnt lgkmcnt(0)
	v_writelane_b32 v254, s6, 9
	s_nop 1
	v_writelane_b32 v254, s7, 10
	v_writelane_b32 v254, s8, 11
	s_nop 1
	v_writelane_b32 v254, s9, 12
	v_writelane_b32 v254, s10, 13
	v_writelane_b32 v254, s11, 14
	v_writelane_b32 v254, s12, 15
	v_writelane_b32 v254, s13, 16
	v_writelane_b32 v254, s14, 17
	v_writelane_b32 v254, s15, 18
	v_writelane_b32 v254, s70, 19
	v_writelane_b32 v254, s72, 20
	s_nop 1
	v_writelane_b32 v254, s73, 21
	v_writelane_b32 v254, s71, 22
	v_writelane_b32 v254, s80, 23
	s_nop 1
	v_writelane_b32 v254, s81, 24
	v_writelane_b32 v254, s82, 25
	s_nop 1
	v_writelane_b32 v254, s83, 26
	v_writelane_b32 v254, s84, 27
	s_nop 1
	v_writelane_b32 v254, s85, 28
	v_writelane_b32 v254, s86, 29
	s_nop 1
	v_writelane_b32 v254, s87, 30
	v_writelane_b32 v254, s88, 31
	s_nop 1
	v_writelane_b32 v254, s89, 32
	v_writelane_b32 v254, s69, 33
	v_writelane_b32 v254, s72, 34
	v_writelane_b32 v254, s21, 35
	v_writelane_b32 v254, s22, 36
	s_nop 1
	v_writelane_b32 v254, s23, 37
	v_writelane_b32 v254, s3, 38
	v_writelane_b32 v254, s4, 39
	s_branch .LBB0_278

.LBB0_550:
	s_add_i32 s41, s41, 1
	v_readlane_b32 s4, v253, 32
	v_readlane_b32 s6, v253, 0
	s_mul_i32 s4, s41, s4
	s_mul_hi_u32 s5, s41, s6
	s_add_i32 s5, s5, s4
	s_mul_i32 s4, s41, s6
	v_readlane_b32 s7, v253, 1
	s_add_u32 s6, s4, s70
	v_readlane_b32 s4, v253, 33
	s_addc_u32 s7, s5, s4
	v_mov_b64_e32 v[2:3], 0x400
	v_cmp_lt_i64_e64 s[4:5], s[6:7], v[2:3]
	v_mov_b64_e32 v[2:3], 0x3ff
	v_cmp_gt_i64_e32 vcc, s[6:7], v[2:3]
	s_cbranch_vccnz .LBB0_552
	s_ashr_i32 s7, s6, 3
	s_lshl_b32 s6, s6, 7
	s_and_b32 s6, s6, 0x380
	s_add_i32 s6, s6, s7
	s_ashr_i32 s13, s6, 31
	s_lshr_b32 s13, s13, 27
	s_add_i32 s13, s6, s13
	s_ashr_i32 s22, s13, 5
	s_xor_b32 s22, s22, 3
	s_andn2_b32 s13, s13, 31
	s_sub_i32 s6, s6, s13
	s_lshl_b32 s13, s22, 3
	s_and_b32 s7, s7, 7
	s_or_b32 s42, s13, s7
	s_ashr_i32 s13, s6, 3
